# tile order: input-projection GEMM also 4 row panels x 8 column tiles per XCD step (on top of FFN-down + output-projection remaps)
# baseline (speedup 1.0000x reference)
;     __host__ __device__ __forceinline__ bool next(int i, Unit& u) const {
;         const long L = (long)i * G + c; if (L >= nwg) return false;
;         int wgid = (int)L; { const int q = nwg / NXCD, r = nwg % NXCD, xcd = wgid % NXCD, off = wgid / NXCD; wgid = (xcd < r ? xcd * (q + 1) : r * (q + 1) + (xcd - r) * q) + off; }
;         const int nig = WGM * nN, gid = wgid / nig, fm = gid * WGM, gsz = (nM - fm) < WGM ? (nM - fm) : WGM;
;         u.pm = fm + ((wgid % nig) % gsz); u.pn = (wgid % nig) / gsz; return true;
;     }
.LBB0_357:
	v_readlane_b32 s0, v254, 26
	v_readlane_b32 s1, v254, 27
	s_andn2_b64 vcc, exec, s[0:1]
	s_cbranch_vccnz .LBB0_552
	s_waitcnt lgkmcnt(0)
	v_mov_b32_e32 v1, v0
	v_readlane_b32 s44, v254, 0
	v_readlane_b32 s4, v254, 11
	s_cmpk_lt_i32 s44, 0x600
	v_readlane_b32 s45, v254, 3
	s_mov_b64 s[12:13], 0
	s_mov_b32 s14, s4
	s_cselect_b64 s[0:1], -1, 0
	s_cmpk_gt_i32 s44, 0x5ff
	v_readfirstlane_b32 s4, v1
	v_readlane_b32 s5, v254, 12
	v_readlane_b32 s6, v254, 13
	v_readlane_b32 s7, v254, 14
	s_cbranch_scc1 .LBB0_360
	s_ashr_i32 s5, s44, 31
	s_lshr_b32 s5, s5, 29
	s_add_i32 s5, s44, s5
	s_ashr_i32 s6, s5, 3
	s_and_b32 s5, s5, -8
	s_sub_i32 s5, s44, s5
	s_cmp_lt_i32 s5, 0
	s_movk_i32 s7, 0xc1
	s_cselect_b32 s7, s7, 0xc0
	s_mul_i32 s5, s5, s7
	s_add_i32 s5, s5, s6
	s_mul_hi_i32 s6, s5, 0x2aaaaaab
	s_lshr_b32 s7, s6, 31
	s_ashr_i32 s6, s6, 5
	s_add_i32 s6, s6, s7
	s_lshl_b32 s7, s6, 3
	s_mulk_i32 s6, 0xc0
	s_sub_i32 s5, s5, s6
	s_bfe_u32 s6, s5, 0x3001c
	s_add_i32 s6, s5, s6
	s_sext_i32_i16 s8, s6
	s_and_b32 s6, s6, 0xfff8
	s_sub_i32 s5, s5, s6
	s_sext_i32_i16 s5, s5
	s_add_i32 s20, s7, s5
	s_ashr_i32 s38, s8, 3
	s_lshr_b32 s5, s38, 2
	s_cmp_ge_u32 s5, 3
	s_cselect_b32 s6, 3, 0
	s_cselect_b32 s7, 4, 0
	s_sub_i32 s5, s5, s6
	s_lshl_b32 s5, s5, 3
	s_and_b32 s6, s38, 3
	s_lshl_b32 s6, s6, 1
	s_add_i32 s5, s5, s6
	s_bfe_u32 s6, s20, 0x10002
	s_add_i32 s38, s5, s6
	s_and_b32 s6, s20, 3
	s_add_i32 s7, s7, s6
	s_and_b32 s20, s20, -8
	s_add_i32 s20, s20, s7

;     __host__ __device__ __forceinline__ bool next(int i, Unit& u) const {
;         const long L = (long)i * G + c; if (L >= nwg) return false;
;         int wgid = (int)L; { const int q = nwg / NXCD, r = nwg % NXCD, xcd = wgid % NXCD, off = wgid / NXCD; wgid = (xcd < r ? xcd * (q + 1) : r * (q + 1) + (xcd - r) * q) + off; }
;         const int nig = WGM * nN, gid = wgid / nig, fm = gid * WGM, gsz = (nM - fm) < WGM ? (nM - fm) : WGM;
;         u.pm = fm + ((wgid % nig) % gsz); u.pn = (wgid % nig) / gsz; return true;
;     }
;     ...
;         const bool has_next = S.next(ui + 1, nxt);
.LBB0_366:
	s_add_i32 s66, s66, 1
	s_mul_i32 s6, s66, s69
	s_mul_hi_u32 s7, s66, s45
	s_add_i32 s7, s7, s6
	s_mul_i32 s6, s66, s45
	s_add_u32 s10, s6, s44
	s_addc_u32 s11, s7, s70
	s_waitcnt lgkmcnt(0)
	v_mov_b64_e32 v[2:3], 0x600
	v_cmp_lt_i64_e64 s[6:7], s[10:11], v[2:3]
	v_mov_b64_e32 v[2:3], 0x5ff
	v_cmp_gt_i64_e32 vcc, s[10:11], v[2:3]
	s_cbranch_vccnz .LBB0_368
	s_ashr_i32 s11, s10, 31
	s_lshr_b32 s11, s11, 29
	s_add_i32 s11, s10, s11
	s_ashr_i32 s28, s11, 3
	s_and_b32 s11, s11, -8
	s_sub_i32 s10, s10, s11
	s_cmp_lt_i32 s10, 0
	s_movk_i32 s11, 0xc1
	s_cselect_b32 s11, s11, 0xc0
	s_mul_i32 s10, s10, s11
	s_add_i32 s10, s10, s28
	s_mul_hi_i32 s11, s10, 0x2aaaaaab
	s_lshr_b32 s28, s11, 31
	s_ashr_i32 s11, s11, 5
	s_add_i32 s11, s11, s28
	s_lshl_b32 s29, s11, 3
	s_sub_i32 s28, 64, s29
	s_min_i32 s30, s28, 8
	s_abs_i32 s28, s30
	v_cvt_f32_u32_e32 v2, s28
	s_sub_i32 s34, 0, s28
	s_mulk_i32 s11, 0xc0
	s_sub_i32 s10, s10, s11
	v_rcp_iflag_f32_e32 v2, v2
	s_abs_i32 s11, s10
	s_xor_b32 s31, s10, s30
	s_ashr_i32 s31, s31, 31
	v_mul_f32_e32 v2, 0x4f7ffffe, v2
	v_cvt_u32_f32_e32 v2, v2
	s_nop 0
	v_readfirstlane_b32 s35, v2
	s_mul_i32 s34, s34, s35
	s_mul_hi_u32 s34, s35, s34
	s_add_i32 s35, s35, s34
	s_mul_hi_u32 s34, s11, s35
	s_mul_i32 s35, s34, s28
	s_sub_i32 s11, s11, s35
	s_add_i32 s36, s34, 1
	s_sub_i32 s35, s11, s28
	s_cmp_ge_u32 s11, s28
	s_cselect_b32 s34, s36, s34
	s_cselect_b32 s11, s35, s11
	s_add_i32 s35, s34, 1
	s_cmp_ge_u32 s11, s28
	s_cselect_b32 s11, s35, s34
	s_xor_b32 s11, s11, s31
	s_sub_i32 s28, s11, s31
	s_mul_i32 s11, s28, s30
	s_sub_i32 s10, s10, s11
	s_add_i32 s30, s29, s10
	s_lshr_b32 s10, s28, 2
	s_cmp_ge_u32 s10, 3
	s_cselect_b32 s11, 3, 0
	s_cselect_b32 s31, 4, 0
	s_sub_i32 s10, s10, s11
	s_lshl_b32 s10, s10, 3
	s_and_b32 s11, s28, 3
	s_lshl_b32 s11, s11, 1
	s_add_i32 s10, s10, s11
	s_bfe_u32 s11, s30, 0x10002
	s_add_i32 s28, s10, s11
	s_and_b32 s11, s30, 3
	s_add_i32 s31, s31, s11
	s_and_b32 s30, s30, -8
	s_add_i32 s30, s30, s31
